# peel + static s_setprio 1 for waves 4-7 during both attention phases
# speedup vs baseline: 1.0092x; 1.0071x over previous
; #define LAS __attribute__((address_space(3)))
; __device__ __forceinline__ unsigned swz(unsigned row) { return ((row & 3u) << 2) | ((row >> 2) & 3u); }
; __device__ __forceinline__ void segment(LAS unsigned char* lds, const bf16* __restrict__ QKV, bf16* __restrict__ Og, float* __restrict__ L2, int bl, int g, int h, int r, int dil, int n0, int cnt, int tid) {
;     const int lane = tid & 63, w = __builtin_amdgcn_readfirstlane(tid >> 6), lq = lane & 15, gq = lane >> 4;
;     const size_t rowbase = (size_t)bl * SEQ + r;
;     const bf16* qcol = QKV + (size_t)g * 3072 + h * 128;
;     const int srow = tid >> 4, sch = tid & 15;
;     const unsigned sdst = 256u * srow + 16u * ((unsigned)sch ^ swz(srow));
;     const unsigned sdstv = VBASE + 256u * srow + 16u * ((unsigned)sch ^ (2u * (srow & 7)));
;     unsigned koff[4], voff[8];
; #pragma unroll
;     for (int s = 0; s < 4; ++s) koff[s] = 256u * lq + 16u * ((unsigned)(4 * s + gq) ^ swz(lq));
;     { const unsigned q4 = lq >> 2, p4 = lq & 3, rowv = 4 * gq + q4;
; #pragma unroll
;       for (int c = 0; c < 8; ++c) voff[c] = 256u * rowv + 16u * ((unsigned)(2 * c + (p4 & 1)) ^ (2u * (rowv & 7))) + 8u * (p4 >> 1); }
;     const float cb = exp2f(-8.0f * (float)(g * 8 + h + 1) / 24.0f) * (float)dil * 1.4426950408889634f;
;     const float basel = -cb * (float)(128 + lq - 4 * gq);
;     v4u kv[8]; bf16x8 qn[4], qf[4];
; __device__ __forceinline__ void phase(LAS unsigned char* lds, const bf16* QKV, bf16* Og, float* L2, int tid) {
;     for (int it = blockIdx.x; it < 768; it += gridDim.x) {
.LBB0_276:
	s_cmp_lt_i32 s84, 3
	s_cselect_b64 s[4:5], -1, 0
	s_add_u32 s2, s82, 0x200000
	s_addc_u32 s3, s83, 0
	v_writelane_b32 v239, s2, 51
	s_and_b64 s[0:1], s[4:5], s[0:1]
	s_andn2_b64 vcc, exec, s[0:1]
	v_writelane_b32 v239, s3, 52
	v_writelane_b32 v239, s80, 53
	s_nop 1
	v_writelane_b32 v239, s81, 54
	v_writelane_b32 v239, s82, 55
	v_writelane_b32 v239, s83, 56
	v_writelane_b32 v239, s84, 57
	v_writelane_b32 v239, s85, 58
	v_writelane_b32 v239, s86, 59
	v_writelane_b32 v239, s87, 60
	s_cbranch_vccnz .LBB0_302
	v_readfirstlane_b32 s99, v154
	s_nop 3
	s_lshr_b32 s99, s99, 6
	s_cmp_ge_u32 s99, 4
	s_cbranch_scc0 .Lattprio_0
	s_setprio 1
.Lattprio_0:
	v_writelane_b32 v239, s4, 61
	s_nop 1
	v_writelane_b32 v239, s5, 62
	s_nop 0
	v_readlane_b32 s0, v239, 0
	s_cmpk_gt_i32 s0, 0x2ff
	s_cbranch_scc1 .LBB0_301
	v_lshlrev_b32_e32 v5, 2, v154
	v_and_b32_e32 v119, 15, v154
	v_bfe_u32 v1, v154, 4, 2
	v_and_b32_e32 v6, 12, v5
	v_bfe_u32 v7, v154, 2, 2
	v_lshrrev_b32_e32 v2, 2, v154
	v_lshlrev_b32_e32 v4, 8, v119
	v_or_b32_e32 v8, v6, v7
	v_bitop3_b32 v6, v6, v1, v7 bitop3:0x36
	v_lshrrev_b32_e32 v122, 4, v154
	v_and_b32_e32 v2, 12, v2
	v_bfe_u32 v3, v154, 6, 2
	v_lshl_or_b32 v123, v6, 4, v4
	v_bitop3_b32 v6, v1, v8, 4 bitop3:0x36
	v_lshlrev_b32_e32 v0, 8, v122
	v_bitop3_b32 v2, v2, v119, v3 bitop3:0x36
	v_lshl_or_b32 v124, v6, 4, v4
	v_bitop3_b32 v6, v1, v8, 8 bitop3:0x36
	v_lshl_or_b32 v125, v6, 4, v4
	v_bitop3_b32 v6, v1, v8, 12 bitop3:0x36
	v_lshl_or_b32 v127, v2, 4, v0
	v_lshlrev_b32_e32 v2, 2, v1
	v_lshl_or_b32 v126, v6, 4, v4
	v_or_b32_e32 v4, v2, v7
	v_lshlrev_b32_e32 v7, 1, v4
	v_and_b32_e32 v6, 1, v154
	v_and_b32_e32 v8, 14, v7
	v_and_b32_e32 v5, 8, v5
	v_lshl_or_b32 v4, v4, 8, v5
	v_or_b32_e32 v5, v8, v6
	v_lshl_or_b32 v128, v5, 4, v4
	v_or_b32_e32 v5, 2, v6
	v_bitop3_b32 v5, v7, v5, 14 bitop3:0x6c
	v_lshl_or_b32 v129, v5, 4, v4
	v_or_b32_e32 v5, 4, v6
	v_bitop3_b32 v5, v7, v5, 14 bitop3:0x6c
	v_lshrrev_b32_e32 v3, 3, v154
	v_lshl_or_b32 v130, v5, 4, v4
	v_or_b32_e32 v5, 6, v6
	v_bitop3_b32 v3, v3, v119, 14 bitop3:0x6c
	v_bitop3_b32 v5, v7, v5, 14 bitop3:0x6c
	v_lshlrev_b32_e32 v3, 4, v3
	v_lshl_or_b32 v131, v5, 4, v4
	v_or_b32_e32 v5, 8, v6
	s_mov_b32 s0, 0x10000
	v_bitop3_b32 v5, v7, v5, 14 bitop3:0x6c
	v_or3_b32 v136, v3, v0, s0
	v_or_b32_e32 v0, 0x80, v119
	v_lshl_or_b32 v132, v5, 4, v4
	v_or_b32_e32 v5, 10, v6
	v_sub_u32_e32 v0, v0, v2
	v_bitop3_b32 v5, v7, v5, 14 bitop3:0x6c
	v_cvt_f32_ubyte0_e32 v137, v0
	v_or_b32_e32 v0, 1, v2
	v_lshl_or_b32 v133, v5, 4, v4
	v_or_b32_e32 v5, 12, v6
	v_cmp_ge_u32_e64 s[4:5], v2, v119
	v_cmp_ge_u32_e64 s[6:7], v0, v119
	v_or_b32_e32 v0, 2, v2
	v_or_b32_e32 v3, 3, v2
	v_cmp_gt_u32_e64 s[12:13], v2, v119
	v_cmp_lt_u32_e64 s[14:15], v2, v119
	v_mbcnt_lo_u32_b32 v2, -1, 0
	v_bitop3_b32 v5, v7, v5, 14 bitop3:0x6c
	v_mbcnt_hi_u32_b32 v2, -1, v2
	v_lshl_or_b32 v134, v5, 4, v4
	v_bitop3_b32 v5, v7, v6, 14 bitop3:0x4e
	v_and_b32_e32 v6, 64, v2
	v_lshl_or_b32 v135, v5, 4, v4
	v_xor_b32_e32 v5, 16, v2
	v_add_u32_e32 v6, 64, v6
	v_cmp_lt_i32_e32 vcc, v5, v6
	v_cmp_ge_u32_e64 s[10:11], v3, v119
	v_cmp_gt_u32_e64 s[18:19], v3, v119
	v_cndmask_b32_e32 v5, v2, v5, vcc
	v_lshlrev_b32_e32 v139, 2, v5
	v_xor_b32_e32 v5, 32, v2
	v_cmp_lt_i32_e32 vcc, v5, v6
	v_mov_b32_e32 v3, 0
	s_mov_b64 s[0:1], 0x7c00000
	v_cndmask_b32_e32 v2, v2, v5, vcc
	v_lshlrev_b32_e32 v140, 2, v2
	v_lshlrev_b32_e32 v2, 4, v1
	v_lshl_add_u64 v[6:7], s[82:83], 0, v[2:3]
	v_cmp_ge_u32_e64 s[8:9], v0, v119
	v_cmp_gt_u32_e64 s[16:17], v0, v119
	v_lshlrev_b32_e32 v0, 3, v119
	v_lshlrev_b32_e32 v4, 3, v1
	v_lshl_add_u64 v[68:69], s[80:81], 0, v[2:3]
	v_lshl_add_u64 v[70:71], v[6:7], 0, s[0:1]
	v_lshlrev_b32_e32 v2, 4, v119
	v_readlane_b32 s0, v239, 0
	v_or_b32_e32 v138, 0xffffff80, v122
	s_mov_b32 s41, 0
	v_cmp_eq_u32_e64 s[2:3], 0, v1
	v_lshl_add_u64 v[72:73], s[82:83], 0, v[2:3]
	v_mov_b32_e32 v141, 0x42800000
	v_lshlrev_b32_e32 v74, 1, v4
	v_mov_b32_e32 v75, v3
	v_lshlrev_b32_e32 v76, 1, v0
	v_mov_b32_e32 v77, v3
	v_mov_b64_e32 v[78:79], 0x2d0000
	v_mov_b64_e32 v[80:81], 0x240000
	v_mov_b64_e32 v[82:83], 0x360000
	v_mov_b64_e32 v[84:85], 0x3f0000
	v_mov_b32_e32 v142, 0xff800000
	s_mov_b32 s25, s0
	v_writelane_b32 v239, s64, 63
	s_nop 1
	v_writelane_b32 v238, s65, 0
	s_branch .LBB0_280

; __device__ __forceinline__ void phase(LAS unsigned char* lds, const bf16* QKV, bf16* Og, float* L2, int tid) {
;     ...
;     }
;     __syncthreads();
.LBB0_301:
	s_setprio 0
	v_readlane_b32 s4, v239, 61
	v_readlane_b32 s20, v239, 44
	v_readlane_b32 s5, v239, 62
	s_waitcnt vmcnt(0)
	s_barrier
	v_readlane_b32 s21, v239, 45

; #define LAS __attribute__((address_space(3)))
; __device__ __forceinline__ unsigned swz(unsigned row) { return ((row & 3u) << 2) | ((row >> 2) & 3u); }
; __device__ __forceinline__ void segment(LAS unsigned char* lds, const bf16* __restrict__ QKV, bf16* __restrict__ Og, float* __restrict__ L2, int bl, int g, int h, int r, int dil, int n0, int cnt, int tid) {
;     const int lane = tid & 63, w = __builtin_amdgcn_readfirstlane(tid >> 6), lq = lane & 15, gq = lane >> 4;
;     const size_t rowbase = (size_t)bl * SEQ + r;
;     const bf16* qcol = QKV + (size_t)g * 3072 + h * 128;
;     const int srow = tid >> 4, sch = tid & 15;
;     const unsigned sdst = 256u * srow + 16u * ((unsigned)sch ^ swz(srow));
;     const unsigned sdstv = VBASE + 256u * srow + 16u * ((unsigned)sch ^ (2u * (srow & 7)));
;     unsigned koff[4], voff[8];
; #pragma unroll
;     for (int s = 0; s < 4; ++s) koff[s] = 256u * lq + 16u * ((unsigned)(4 * s + gq) ^ swz(lq));
;     { const unsigned q4 = lq >> 2, p4 = lq & 3, rowv = 4 * gq + q4;
; #pragma unroll
;       for (int c = 0; c < 8; ++c) voff[c] = 256u * rowv + 16u * ((unsigned)(2 * c + (p4 & 1)) ^ (2u * (rowv & 7))) + 8u * (p4 >> 1); }
;     const float cb = exp2f(-8.0f * (float)(g * 8 + h + 1) / 24.0f) * (float)dil * 1.4426950408889634f;
;     const float basel = -cb * (float)(128 + lq - 4 * gq);
;     v4u kv[8]; bf16x8 qn[4], qf[4];
; __device__ __forceinline__ void phase(LAS unsigned char* lds, const bf16* QKV, bf16* Og, float* L2, int tid) {
;     for (int it = blockIdx.x; it < 768; it += gridDim.x) {
.LBB0_430:
	s_cmp_lt_i32 s84, 5
	s_cselect_b64 s[2:3], -1, 0
	s_and_b64 s[0:1], s[2:3], s[0:1]
	s_andn2_b64 vcc, exec, s[0:1]
	s_cbranch_vccnz .LBB0_456
	v_readfirstlane_b32 s99, v154
	s_nop 3
	s_lshr_b32 s99, s99, 6
	s_cmp_ge_u32 s99, 4
	s_cbranch_scc0 .Lattprio_1
	s_setprio 1
.Lattprio_1:
	v_writelane_b32 v239, s2, 63
	s_nop 0
	v_readlane_b32 s0, v239, 0
	s_cmpk_gt_i32 s0, 0x2ff
	v_writelane_b32 v238, s3, 0
	s_cbranch_scc1 .LBB0_455
	v_lshlrev_b32_e32 v5, 2, v154
	v_and_b32_e32 v119, 15, v154
	v_bfe_u32 v1, v154, 4, 2
	v_and_b32_e32 v6, 12, v5
	v_bfe_u32 v7, v154, 2, 2
	v_lshrrev_b32_e32 v2, 2, v154
	v_lshlrev_b32_e32 v4, 8, v119
	v_or_b32_e32 v8, v6, v7
	v_bitop3_b32 v6, v6, v1, v7 bitop3:0x36
	v_lshrrev_b32_e32 v122, 4, v154
	v_and_b32_e32 v2, 12, v2
	v_bfe_u32 v3, v154, 6, 2
	v_lshl_or_b32 v123, v6, 4, v4
	v_bitop3_b32 v6, v1, v8, 4 bitop3:0x36
	v_lshlrev_b32_e32 v0, 8, v122
	v_bitop3_b32 v2, v2, v119, v3 bitop3:0x36
	v_lshl_or_b32 v124, v6, 4, v4
	v_bitop3_b32 v6, v1, v8, 8 bitop3:0x36
	v_lshl_or_b32 v125, v6, 4, v4
	v_bitop3_b32 v6, v1, v8, 12 bitop3:0x36
	v_lshl_or_b32 v127, v2, 4, v0
	v_lshlrev_b32_e32 v2, 2, v1
	v_lshl_or_b32 v126, v6, 4, v4
	v_or_b32_e32 v4, v2, v7
	v_lshlrev_b32_e32 v7, 1, v4
	v_and_b32_e32 v6, 1, v154
	v_and_b32_e32 v8, 14, v7
	v_and_b32_e32 v5, 8, v5
	v_lshl_or_b32 v4, v4, 8, v5
	v_or_b32_e32 v5, v8, v6
	v_lshl_or_b32 v128, v5, 4, v4
	v_or_b32_e32 v5, 2, v6
	v_bitop3_b32 v5, v7, v5, 14 bitop3:0x6c
	v_lshl_or_b32 v129, v5, 4, v4
	v_or_b32_e32 v5, 4, v6
	v_bitop3_b32 v5, v7, v5, 14 bitop3:0x6c
	v_lshrrev_b32_e32 v3, 3, v154
	v_lshl_or_b32 v130, v5, 4, v4
	v_or_b32_e32 v5, 6, v6
	v_bitop3_b32 v3, v3, v119, 14 bitop3:0x6c
	v_bitop3_b32 v5, v7, v5, 14 bitop3:0x6c
	v_lshlrev_b32_e32 v3, 4, v3
	v_lshl_or_b32 v131, v5, 4, v4
	v_or_b32_e32 v5, 8, v6
	s_mov_b32 s0, 0x10000
	v_bitop3_b32 v5, v7, v5, 14 bitop3:0x6c
	v_or3_b32 v136, v3, v0, s0
	v_or_b32_e32 v0, 0x80, v119
	v_lshl_or_b32 v132, v5, 4, v4
	v_or_b32_e32 v5, 10, v6
	v_sub_u32_e32 v0, v0, v2
	v_bitop3_b32 v5, v7, v5, 14 bitop3:0x6c
	v_cvt_f32_ubyte0_e32 v137, v0
	v_or_b32_e32 v0, 1, v2
	v_lshl_or_b32 v133, v5, 4, v4
	v_or_b32_e32 v5, 12, v6
	v_cmp_ge_u32_e64 s[4:5], v2, v119
	v_cmp_ge_u32_e64 s[6:7], v0, v119
	v_or_b32_e32 v0, 2, v2
	v_or_b32_e32 v3, 3, v2
	v_cmp_gt_u32_e64 s[12:13], v2, v119
	v_cmp_lt_u32_e64 s[14:15], v2, v119
	v_mbcnt_lo_u32_b32 v2, -1, 0
	v_bitop3_b32 v5, v7, v5, 14 bitop3:0x6c
	v_mbcnt_hi_u32_b32 v2, -1, v2
	v_lshl_or_b32 v134, v5, 4, v4
	v_bitop3_b32 v5, v7, v6, 14 bitop3:0x4e
	v_and_b32_e32 v6, 64, v2
	v_lshl_or_b32 v135, v5, 4, v4
	v_xor_b32_e32 v5, 16, v2
	v_add_u32_e32 v6, 64, v6
	v_cmp_lt_i32_e32 vcc, v5, v6
	v_cmp_ge_u32_e64 s[10:11], v3, v119
	v_cmp_gt_u32_e64 s[18:19], v3, v119
	v_cndmask_b32_e32 v5, v2, v5, vcc
	v_lshlrev_b32_e32 v139, 2, v5
	v_xor_b32_e32 v5, 32, v2
	v_cmp_lt_i32_e32 vcc, v5, v6
	v_mov_b32_e32 v3, 0
	s_mov_b64 s[0:1], 0x7c00000
	v_cndmask_b32_e32 v2, v2, v5, vcc
	v_lshlrev_b32_e32 v140, 2, v2
	v_lshlrev_b32_e32 v2, 4, v1
	v_lshl_add_u64 v[6:7], s[82:83], 0, v[2:3]
	v_cmp_ge_u32_e64 s[8:9], v0, v119
	v_cmp_gt_u32_e64 s[16:17], v0, v119
	v_lshlrev_b32_e32 v0, 3, v119
	v_lshlrev_b32_e32 v4, 3, v1
	v_lshl_add_u64 v[68:69], s[80:81], 0, v[2:3]
	v_lshl_add_u64 v[70:71], v[6:7], 0, s[0:1]
	v_lshlrev_b32_e32 v2, 4, v119
	v_readlane_b32 s0, v239, 0
	v_or_b32_e32 v138, 0xffffff80, v122
	s_mov_b32 s41, 0
	v_cmp_eq_u32_e64 s[2:3], 0, v1
	v_lshl_add_u64 v[72:73], s[82:83], 0, v[2:3]
	v_mov_b32_e32 v141, 0x42800000
	v_lshlrev_b32_e32 v74, 1, v4
	v_mov_b32_e32 v75, v3
	v_lshlrev_b32_e32 v76, 1, v0
	v_mov_b32_e32 v77, v3
	v_mov_b64_e32 v[78:79], 0x2d0000
	v_mov_b64_e32 v[80:81], 0x240000
	v_mov_b64_e32 v[82:83], 0x360000
	v_mov_b64_e32 v[84:85], 0x3f0000
	v_mov_b32_e32 v142, 0xff800000
	s_mov_b32 s25, s0
	s_branch .LBB0_434

; __device__ __forceinline__ void phase(LAS unsigned char* lds, const bf16* QKV, bf16* Og, float* L2, int tid) {
;     ...
;     }
;     __syncthreads();
.LBB0_455:
	s_setprio 0
	v_readlane_b32 s2, v239, 63
	v_readlane_b32 s20, v239, 44
	v_readlane_b32 s3, v238, 0
	s_waitcnt vmcnt(0)
	s_barrier
	v_readlane_b32 s21, v239, 45
